# v081 + per-round tile rotation in in-proj and K/V+Q projection phases (balanced heavy/light epilogue mix per WG)
# baseline (speedup 1.0000x reference)
.LBB0_215:
	s_ashr_i32 s7, s7, 3
	s_lshr_b32 s98, s7, 5
	s_lshl_b32 s98, s98, 1
	s_add_i32 s98, s98, s7
	s_and_b32 s98, s98, 31
	s_and_b32 s7, s7, 0xffffffe0
	s_or_b32 s7, s7, s98
	s_add_i32 s7, s25, s7
	s_ashr_i32 s22, s7, 31
	s_lshr_b32 s22, s22, 29
	s_add_i32 s22, s7, s22
	s_ashr_i32 s23, s22, 3
	s_and_b32 s22, s22, -8
	s_sub_i32 s7, s7, s22
	s_mov_b32 s22, s7
	s_mov_b32 s24, s23

.Lph217_w:
	s_nop 0
	s_nop 0
	s_nop 0
	s_nop 0
	s_waitcnt vmcnt(8)
	s_waitcnt lgkmcnt(0)
	s_setprio 1
	s_barrier
	v_mfma_f32_16x16x32_bf16 v[124:127], v[146:149], v[186:189], v[124:127]
	v_mfma_f32_16x16x32_bf16 v[120:123], v[162:165], v[186:189], v[120:123]
	v_mfma_f32_16x16x32_bf16 v[108:111], v[146:149], v[194:197], v[108:111]
	v_mfma_f32_16x16x32_bf16 v[104:107], v[162:165], v[194:197], v[104:107]
	v_mfma_f32_16x16x32_bf16 v[92:95], v[146:149], v[202:205], v[92:95]
	v_mfma_f32_16x16x32_bf16 v[88:91], v[162:165], v[202:205], v[88:91]
	v_mfma_f32_16x16x32_bf16 v[76:79], v[146:149], v[210:213], v[76:79]
	v_mfma_f32_16x16x32_bf16 v[72:75], v[162:165], v[210:213], v[72:75]
	v_mfma_f32_16x16x32_bf16 v[124:127], v[158:161], v[190:193], v[124:127]
	v_mfma_f32_16x16x32_bf16 v[120:123], v[166:169], v[190:193], v[120:123]
	v_mfma_f32_16x16x32_bf16 v[108:111], v[158:161], v[198:201], v[108:111]
	v_mfma_f32_16x16x32_bf16 v[104:107], v[166:169], v[198:201], v[104:107]
	v_mfma_f32_16x16x32_bf16 v[92:95], v[158:161], v[206:209], v[92:95]
	v_mfma_f32_16x16x32_bf16 v[88:91], v[166:169], v[206:209], v[88:91]
	v_mfma_f32_16x16x32_bf16 v[76:79], v[158:161], v[214:217], v[76:79]
	v_mfma_f32_16x16x32_bf16 v[72:75], v[166:169], v[214:217], v[72:75]
	s_setprio 0
	s_setprio 1
	v_mfma_f32_16x16x32_bf16 v[116:119], v[170:173], v[186:189], v[116:119]
	v_mfma_f32_16x16x32_bf16 v[112:115], v[178:181], v[186:189], v[112:115]
	v_mfma_f32_16x16x32_bf16 v[100:103], v[170:173], v[194:197], v[100:103]
	v_mfma_f32_16x16x32_bf16 v[96:99], v[178:181], v[194:197], v[96:99]
	v_mfma_f32_16x16x32_bf16 v[84:87], v[170:173], v[202:205], v[84:87]
	v_mfma_f32_16x16x32_bf16 v[80:83], v[178:181], v[202:205], v[80:83]
	v_mfma_f32_16x16x32_bf16 v[68:71], v[170:173], v[210:213], v[68:71]
	v_mfma_f32_16x16x32_bf16 v[64:67], v[178:181], v[210:213], v[64:67]
	v_mfma_f32_16x16x32_bf16 v[116:119], v[174:177], v[190:193], v[116:119]
	v_mfma_f32_16x16x32_bf16 v[112:115], v[182:185], v[190:193], v[112:115]
	v_mfma_f32_16x16x32_bf16 v[100:103], v[174:177], v[198:201], v[100:103]
	v_mfma_f32_16x16x32_bf16 v[96:99], v[182:185], v[198:201], v[96:99]
	v_mfma_f32_16x16x32_bf16 v[84:87], v[174:177], v[206:209], v[84:87]
	v_mfma_f32_16x16x32_bf16 v[80:83], v[182:185], v[206:209], v[80:83]
	v_mfma_f32_16x16x32_bf16 v[68:71], v[174:177], v[214:217], v[68:71]
	v_mfma_f32_16x16x32_bf16 v[64:67], v[182:185], v[214:217], v[64:67]
	s_barrier
	s_setprio 0
	s_add_i32 s72, s65, s43
	v_lshl_add_u64 v[150:151], s[36:37], 0, v[130:131]
	s_mov_b32 m0, s72
	s_nop 0
	global_load_lds_dwordx4 v[150:151], off
	s_add_i32 m0, s72, 0x2000
	s_add_u32 s72, s36, 0x40000
	v_lshl_add_u64 v[218:219], s[36:37], 0, v[134:135]
	s_addc_u32 s73, s37, 0
	s_add_i32 s74, s67, s43
	global_load_lds_dwordx4 v[218:219], off
	v_lshl_add_u64 v[220:221], s[72:73], 0, v[130:131]
	s_mov_b32 m0, s74
	v_lshl_add_u64 v[222:223], s[38:39], 0, v[132:133]
	global_load_lds_dwordx4 v[220:221], off
	v_lshl_add_u64 v[220:221], s[72:73], 0, v[134:135]
	s_add_i32 m0, s74, 0x2000
	s_nop 0
	global_load_lds_dwordx4 v[220:221], off
	v_lshl_add_u64 v[220:221], s[38:39], 0, v[128:129]
	s_mov_b32 m0, s31
	s_nop 0
	global_load_lds_dwordx4 v[220:221], off
	s_mov_b32 m0, s46
	s_nop 0
	global_load_lds_dwordx4 v[222:223], off
	ds_read_b128 v[186:189], v157 offset:16384
	ds_read_b128 v[190:193], v157 offset:17408
	ds_read_b128 v[194:197], v157 offset:18432
	ds_read_b128 v[198:201], v157 offset:19456
	ds_read_b128 v[202:205], v157 offset:20480
	ds_read_b128 v[206:209], v157 offset:21504
	ds_read_b128 v[210:213], v157 offset:22528
	ds_read_b128 v[214:217], v157 offset:23552
	s_nop 0
	s_waitcnt vmcnt(8)
	s_waitcnt lgkmcnt(0)
	s_setprio 1
	s_barrier
	v_mfma_f32_16x16x32_bf16 v[60:63], v[146:149], v[186:189], v[60:63]
	v_mfma_f32_16x16x32_bf16 v[56:59], v[162:165], v[186:189], v[56:59]
	v_mfma_f32_16x16x32_bf16 v[44:47], v[146:149], v[194:197], v[44:47]
	v_mfma_f32_16x16x32_bf16 v[40:43], v[162:165], v[194:197], v[40:43]
	v_mfma_f32_16x16x32_bf16 v[28:31], v[146:149], v[202:205], v[28:31]
	v_mfma_f32_16x16x32_bf16 v[24:27], v[162:165], v[202:205], v[24:27]
	v_mfma_f32_16x16x32_bf16 v[12:15], v[146:149], v[210:213], v[12:15]
	v_mfma_f32_16x16x32_bf16 v[8:11], v[162:165], v[210:213], v[8:11]
	v_mfma_f32_16x16x32_bf16 v[60:63], v[158:161], v[190:193], v[60:63]
	v_mfma_f32_16x16x32_bf16 v[56:59], v[166:169], v[190:193], v[56:59]
	v_mfma_f32_16x16x32_bf16 v[44:47], v[158:161], v[198:201], v[44:47]
	v_mfma_f32_16x16x32_bf16 v[40:43], v[166:169], v[198:201], v[40:43]
	v_mfma_f32_16x16x32_bf16 v[28:31], v[158:161], v[206:209], v[28:31]
	v_mfma_f32_16x16x32_bf16 v[24:27], v[166:169], v[206:209], v[24:27]
	v_mfma_f32_16x16x32_bf16 v[12:15], v[158:161], v[214:217], v[12:15]
	v_mfma_f32_16x16x32_bf16 v[8:11], v[166:169], v[214:217], v[8:11]
	s_setprio 0
	s_setprio 1
	v_mfma_f32_16x16x32_bf16 v[52:55], v[170:173], v[186:189], v[52:55]
	v_mfma_f32_16x16x32_bf16 v[48:51], v[178:181], v[186:189], v[48:51]
	v_mfma_f32_16x16x32_bf16 v[36:39], v[170:173], v[194:197], v[36:39]
	v_mfma_f32_16x16x32_bf16 v[32:35], v[178:181], v[194:197], v[32:35]
	v_mfma_f32_16x16x32_bf16 v[20:23], v[170:173], v[202:205], v[20:23]
	v_mfma_f32_16x16x32_bf16 v[16:19], v[178:181], v[202:205], v[16:19]
	v_mfma_f32_16x16x32_bf16 v[4:7], v[170:173], v[210:213], v[4:7]
	v_mfma_f32_16x16x32_bf16 v[0:3], v[178:181], v[210:213], v[0:3]
	v_mfma_f32_16x16x32_bf16 v[52:55], v[174:177], v[190:193], v[52:55]
	v_mfma_f32_16x16x32_bf16 v[48:51], v[182:185], v[190:193], v[48:51]
	v_mfma_f32_16x16x32_bf16 v[36:39], v[174:177], v[198:201], v[36:39]
	v_mfma_f32_16x16x32_bf16 v[32:35], v[182:185], v[198:201], v[32:35]
	v_mfma_f32_16x16x32_bf16 v[20:23], v[174:177], v[206:209], v[20:23]
	v_mfma_f32_16x16x32_bf16 v[16:19], v[182:185], v[206:209], v[16:19]
	v_mfma_f32_16x16x32_bf16 v[4:7], v[174:177], v[214:217], v[4:7]
	v_mfma_f32_16x16x32_bf16 v[0:3], v[182:185], v[214:217], v[0:3]
	s_barrier
	s_setprio 0
	s_add_i32 s72, 0, 0x18000
	s_add_i32 s73, 0, 0x1c000
	s_add_u32 s38, s38, 0x40000
	s_addc_u32 s39, s39, 0
	s_mov_b32 m0, s47
	v_lshl_add_u64 v[224:225], s[38:39], 0, v[128:129]
	global_load_lds_dwordx4 v[224:225], off
	v_lshl_add_u64 v[224:225], s[38:39], 0, v[132:133]
	s_mov_b32 m0, s48
	s_nop 0
	global_load_lds_dwordx4 v[224:225], off
	v_add_u32_e32 v136, s72, v153
	ds_read_b128 v[146:149], v136
	ds_read_b128 v[158:161], v136 offset:1024
	ds_read_b128 v[162:165], v136 offset:2048
	ds_read_b128 v[166:169], v136 offset:3072
	v_add_u32_e32 v136, s73, v153
	ds_read_b128 v[170:173], v136
	ds_read_b128 v[174:177], v136 offset:1024
	ds_read_b128 v[178:181], v136 offset:2048
	ds_read_b128 v[182:185], v136 offset:3072
	ds_read_b128 v[186:189], v157 offset:32768
	ds_read_b128 v[190:193], v157 offset:33792
	ds_read_b128 v[194:197], v157 offset:34816
	ds_read_b128 v[198:201], v157 offset:35840
	ds_read_b128 v[202:205], v157 offset:36864
	ds_read_b128 v[206:209], v157 offset:37888
	ds_read_b128 v[210:213], v157 offset:38912
	ds_read_b128 v[214:217], v157 offset:39936
	s_waitcnt vmcnt(8)
	s_waitcnt lgkmcnt(0)
	s_setprio 1
	s_barrier
	v_mfma_f32_16x16x32_bf16 v[124:127], v[146:149], v[186:189], v[124:127]
	v_mfma_f32_16x16x32_bf16 v[120:123], v[162:165], v[186:189], v[120:123]
	v_mfma_f32_16x16x32_bf16 v[108:111], v[146:149], v[194:197], v[108:111]
	v_mfma_f32_16x16x32_bf16 v[104:107], v[162:165], v[194:197], v[104:107]
	v_mfma_f32_16x16x32_bf16 v[92:95], v[146:149], v[202:205], v[92:95]
	v_mfma_f32_16x16x32_bf16 v[88:91], v[162:165], v[202:205], v[88:91]
	v_mfma_f32_16x16x32_bf16 v[76:79], v[146:149], v[210:213], v[76:79]
	v_mfma_f32_16x16x32_bf16 v[72:75], v[162:165], v[210:213], v[72:75]
	v_mfma_f32_16x16x32_bf16 v[124:127], v[158:161], v[190:193], v[124:127]
	v_mfma_f32_16x16x32_bf16 v[120:123], v[166:169], v[190:193], v[120:123]
	v_mfma_f32_16x16x32_bf16 v[108:111], v[158:161], v[198:201], v[108:111]
	v_mfma_f32_16x16x32_bf16 v[104:107], v[166:169], v[198:201], v[104:107]
	v_mfma_f32_16x16x32_bf16 v[92:95], v[158:161], v[206:209], v[92:95]
	v_mfma_f32_16x16x32_bf16 v[88:91], v[166:169], v[206:209], v[88:91]
	v_mfma_f32_16x16x32_bf16 v[76:79], v[158:161], v[214:217], v[76:79]
	v_mfma_f32_16x16x32_bf16 v[72:75], v[166:169], v[214:217], v[72:75]
	s_setprio 0
	s_setprio 1
	v_mfma_f32_16x16x32_bf16 v[116:119], v[170:173], v[186:189], v[116:119]
	v_mfma_f32_16x16x32_bf16 v[112:115], v[178:181], v[186:189], v[112:115]
	v_mfma_f32_16x16x32_bf16 v[100:103], v[170:173], v[194:197], v[100:103]
	v_mfma_f32_16x16x32_bf16 v[96:99], v[178:181], v[194:197], v[96:99]
	v_mfma_f32_16x16x32_bf16 v[84:87], v[170:173], v[202:205], v[84:87]
	v_mfma_f32_16x16x32_bf16 v[80:83], v[178:181], v[202:205], v[80:83]
	v_mfma_f32_16x16x32_bf16 v[68:71], v[170:173], v[210:213], v[68:71]
	v_mfma_f32_16x16x32_bf16 v[64:67], v[178:181], v[210:213], v[64:67]
	v_mfma_f32_16x16x32_bf16 v[116:119], v[174:177], v[190:193], v[116:119]
	v_mfma_f32_16x16x32_bf16 v[112:115], v[182:185], v[190:193], v[112:115]
	v_mfma_f32_16x16x32_bf16 v[100:103], v[174:177], v[198:201], v[100:103]
	v_mfma_f32_16x16x32_bf16 v[96:99], v[182:185], v[198:201], v[96:99]
	v_mfma_f32_16x16x32_bf16 v[84:87], v[174:177], v[206:209], v[84:87]
	v_mfma_f32_16x16x32_bf16 v[80:83], v[182:185], v[206:209], v[80:83]
	v_mfma_f32_16x16x32_bf16 v[68:71], v[174:177], v[214:217], v[68:71]
	v_mfma_f32_16x16x32_bf16 v[64:67], v[182:185], v[214:217], v[64:67]
	s_barrier
	s_setprio 0
	s_add_i32 s38, s72, s43
	v_lshl_add_u64 v[150:151], v[150:151], 0, s[12:13]
	s_mov_b32 m0, s38
	s_nop 0
	global_load_lds_dwordx4 v[150:151], off
	s_add_i32 m0, s38, 0x2000
	s_add_u32 s36, s36, 0x40080
	v_lshl_add_u64 v[150:151], v[218:219], 0, s[12:13]
	s_addc_u32 s37, s37, 0
	s_add_i32 s38, s73, s43
	global_load_lds_dwordx4 v[150:151], off
	v_lshl_add_u64 v[150:151], s[36:37], 0, v[130:131]
	s_mov_b32 m0, s38
	s_nop 0
	global_load_lds_dwordx4 v[150:151], off
	v_lshl_add_u64 v[150:151], s[36:37], 0, v[134:135]
	s_add_i32 m0, s38, 0x2000
	s_nop 0
	global_load_lds_dwordx4 v[150:151], off
	v_lshl_add_u64 v[150:151], v[220:221], 0, s[12:13]
	s_mov_b32 m0, s60
	s_nop 0
	global_load_lds_dwordx4 v[150:151], off
	v_lshl_add_u64 v[150:151], v[222:223], 0, s[12:13]
	s_mov_b32 m0, s61
	s_nop 0
	global_load_lds_dwordx4 v[150:151], off
	ds_read_b128 v[186:189], v157 offset:49152
	ds_read_b128 v[190:193], v157 offset:50176
	ds_read_b128 v[194:197], v157 offset:51200
	ds_read_b128 v[198:201], v157 offset:52224
	ds_read_b128 v[202:205], v157 offset:53248
	ds_read_b128 v[206:209], v157 offset:54272
	ds_read_b128 v[210:213], v157 offset:55296
	ds_read_b128 v[214:217], v157 offset:56320
	s_waitcnt vmcnt(8)
	s_waitcnt lgkmcnt(0)
	s_setprio 1
	s_barrier
	v_mfma_f32_16x16x32_bf16 v[60:63], v[146:149], v[186:189], v[60:63]
	v_mfma_f32_16x16x32_bf16 v[56:59], v[162:165], v[186:189], v[56:59]
	v_mfma_f32_16x16x32_bf16 v[44:47], v[146:149], v[194:197], v[44:47]
	v_mfma_f32_16x16x32_bf16 v[40:43], v[162:165], v[194:197], v[40:43]
	v_mfma_f32_16x16x32_bf16 v[28:31], v[146:149], v[202:205], v[28:31]
	v_mfma_f32_16x16x32_bf16 v[24:27], v[162:165], v[202:205], v[24:27]
	v_mfma_f32_16x16x32_bf16 v[12:15], v[146:149], v[210:213], v[12:15]
	v_mfma_f32_16x16x32_bf16 v[8:11], v[162:165], v[210:213], v[8:11]
	v_mfma_f32_16x16x32_bf16 v[60:63], v[158:161], v[190:193], v[60:63]
	v_mfma_f32_16x16x32_bf16 v[56:59], v[166:169], v[190:193], v[56:59]
	v_mfma_f32_16x16x32_bf16 v[44:47], v[158:161], v[198:201], v[44:47]
	v_mfma_f32_16x16x32_bf16 v[40:43], v[166:169], v[198:201], v[40:43]
	v_mfma_f32_16x16x32_bf16 v[28:31], v[158:161], v[206:209], v[28:31]
	v_mfma_f32_16x16x32_bf16 v[24:27], v[166:169], v[206:209], v[24:27]
	v_mfma_f32_16x16x32_bf16 v[12:15], v[158:161], v[214:217], v[12:15]
	v_mfma_f32_16x16x32_bf16 v[8:11], v[166:169], v[214:217], v[8:11]
	s_setprio 0
	s_setprio 1
	v_mfma_f32_16x16x32_bf16 v[52:55], v[170:173], v[186:189], v[52:55]
	v_mfma_f32_16x16x32_bf16 v[48:51], v[178:181], v[186:189], v[48:51]
	v_mfma_f32_16x16x32_bf16 v[36:39], v[170:173], v[194:197], v[36:39]
	v_mfma_f32_16x16x32_bf16 v[32:35], v[178:181], v[194:197], v[32:35]
	v_mfma_f32_16x16x32_bf16 v[20:23], v[170:173], v[202:205], v[20:23]
	v_mfma_f32_16x16x32_bf16 v[16:19], v[178:181], v[202:205], v[16:19]
	v_mfma_f32_16x16x32_bf16 v[4:7], v[170:173], v[210:213], v[4:7]
	v_mfma_f32_16x16x32_bf16 v[0:3], v[178:181], v[210:213], v[0:3]
	v_mfma_f32_16x16x32_bf16 v[52:55], v[174:177], v[190:193], v[52:55]
	v_mfma_f32_16x16x32_bf16 v[48:51], v[182:185], v[190:193], v[48:51]
	v_mfma_f32_16x16x32_bf16 v[36:39], v[174:177], v[198:201], v[36:39]
	v_mfma_f32_16x16x32_bf16 v[32:35], v[182:185], v[198:201], v[32:35]
	v_mfma_f32_16x16x32_bf16 v[20:23], v[174:177], v[206:209], v[20:23]
	v_mfma_f32_16x16x32_bf16 v[16:19], v[182:185], v[206:209], v[16:19]
	v_mfma_f32_16x16x32_bf16 v[4:7], v[174:177], v[214:217], v[4:7]
	v_mfma_f32_16x16x32_bf16 v[0:3], v[182:185], v[214:217], v[0:3]
	s_barrier
	s_setprio 0
	s_add_i32 s71, s71, 2
	s_add_u32 s34, s34, 0x100
	s_addc_u32 s35, s35, 0
	s_add_u32 s69, s69, 0x100
	s_addc_u32 s70, s70, 0
	s_cmp_gt_u32 s71, 13
	s_cbranch_scc0 .LBB0_217
	s_and_b64 vcc, exec, s[14:15]
	s_cbranch_vccz .LBB0_220
	s_barrier

.LBB0_720:
	s_add_i32 s73, s73, 1
	s_mul_i32 s6, s73, s84
	s_mul_hi_u32 s7, s73, s85
	s_add_i32 s7, s7, s6
	s_mul_i32 s6, s73, s85
	s_add_u32 s42, s6, s33
	s_addc_u32 s43, s7, s86
	v_mov_b64_e32 v[0:1], 0x900
	v_cmp_lt_i64_e64 s[6:7], s[42:43], v[0:1]
	v_mov_b64_e32 v[0:1], 0x8ff
	v_cmp_gt_i64_e32 vcc, s[42:43], v[0:1]
	s_cbranch_vccnz .LBB0_722
	s_ashr_i32 s9, s42, 31
	s_lshr_b32 s9, s9, 29
	s_add_i32 s9, s42, s9
	s_ashr_i32 s38, s9, 3
	s_lshr_b32 s98, s38, 5
	s_add_i32 s98, s98, s38
	s_and_b32 s98, s98, 31
	s_and_b32 s38, s38, 0xffffffe0
	s_or_b32 s38, s38, s98
	s_and_b32 s9, s9, -8
	s_sub_i32 s9, s42, s9
	s_cmp_lt_i32 s9, 0
	s_cselect_b32 s39, s87, 0x120
	s_mul_i32 s9, s9, s39
	s_add_i32 s9, s9, s38
	s_mul_hi_i32 s38, s9, 0x38e38e39
	s_lshr_b32 s39, s38, 31
	s_ashr_i32 s38, s38, 2
	s_add_i32 s39, s38, s39
	s_mul_i32 s41, s39, 18
	s_sub_i32 s9, s9, s41
	s_mov_b32 s38, s9
	s_mov_b32 s40, s39
